# 16x16x32 GEMM loop; loader waves issue LDS fragment reads before their LDS-DMA burst
# baseline (speedup 1.0000x reference)
.Lgk_main:
	s_bitcmp1_b32 s34, 0
	s_cselect_b32 s21, 0, 0xec00
	s_cselect_b32 s5, 0xec00, 0
	s_add_i32 s5, s5, s4
	v_add_u32_e32 v172, s21, v204
	v_add_u32_e32 v173, s21, v206
	v_add_u32_e32 v174, s21, v205
	v_add_u32_e32 v175, s21, v207
	ds_read_b128 v[208:211], v173
	ds_read_b128 v[212:215], v173 offset:2048
	ds_read_b128 v[216:219], v173 offset:4096
	ds_read_b128 v[220:223], v173 offset:6144
	ds_read_b128 v[148:151], v172
	ds_read_b128 v[152:155], v172 offset:2048
	ds_read_b128 v[156:159], v172 offset:4096
	ds_read_b128 v[160:163], v172 offset:6144
	ds_read_b128 v[164:167], v172 offset:8192
	ds_read_b128 v[168:171], v172 offset:10240
	s_cmp_lt_u32 s12, 4
	s_cbranch_scc0 .Lgk_nl
	s_mov_b32 m0, s5
	v_lshl_add_u64 v[176:177], v[100:101], 0, s[2:3]
	global_load_lds_dwordx4 v[176:177], off
	s_add_i32 m0, s5, 0x1000
	v_lshl_add_u64 v[176:177], v[176:177], 0, s[8:9]
	global_load_lds_dwordx4 v[176:177], off
	s_add_i32 m0, s5, 0x2000
	v_lshl_add_u64 v[176:177], v[104:105], 0, s[2:3]
	global_load_lds_dwordx4 v[176:177], off
	s_add_i32 m0, s5, 0x3000
	v_lshl_add_u64 v[176:177], v[176:177], 0, s[8:9]
	global_load_lds_dwordx4 v[176:177], off
	s_add_i32 m0, s5, 0x4000
	v_lshl_add_u64 v[176:177], v[102:103], 0, s[2:3]
	global_load_lds_dwordx4 v[176:177], off
	s_add_i32 m0, s5, 0x5000
	v_lshl_add_u64 v[176:177], v[176:177], 0, s[8:9]
	global_load_lds_dwordx4 v[176:177], off
	s_add_i32 m0, s5, 0x6000
	v_lshl_add_u64 v[176:177], v[106:107], 0, s[2:3]
	global_load_lds_dwordx4 v[176:177], off
	s_add_i32 m0, s5, 0x7000
	v_lshl_add_u64 v[176:177], v[176:177], 0, s[10:11]
	global_load_lds_dwordx4 v[176:177], off
	s_add_i32 m0, s5, 0x8000
	v_lshl_add_u64 v[176:177], v[112:113], 0, s[2:3]
	global_load_lds_dwordx4 v[176:177], off
	s_add_i32 m0, s5, 0x9000
	v_lshl_add_u64 v[176:177], v[176:177], 0, s[10:11]
	global_load_lds_dwordx4 v[176:177], off
	s_add_i32 m0, s5, 0xa000
	v_lshl_add_u64 v[176:177], v[108:109], 0, s[2:3]
	global_load_lds_dwordx4 v[176:177], off
	s_add_i32 m0, s5, 0xb000
	v_lshl_add_u64 v[176:177], v[176:177], 0, s[10:11]
	global_load_lds_dwordx4 v[176:177], off
	s_add_i32 m0, s5, 0xc000
	v_lshl_add_u64 v[176:177], v[110:111], 0, s[2:3]
	global_load_lds_dwordx4 v[176:177], off
	s_add_i32 m0, s5, 0xd000
	v_lshl_add_u64 v[176:177], v[176:177], 0, s[10:11]
	global_load_lds_dwordx4 v[176:177], off
.Lgk_nl:
	s_waitcnt lgkmcnt(5)
	v_mfma_f32_16x16x32_bf16 v[82:85], v[148:151], v[208:211], v[82:85]
	v_mfma_f32_16x16x32_bf16 v[86:89], v[148:151], v[212:215], v[86:89]
	v_mfma_f32_16x16x32_bf16 v[66:69], v[148:151], v[216:219], v[66:69]
	v_mfma_f32_16x16x32_bf16 v[70:73], v[148:151], v[220:223], v[70:73]
	ds_read_b128 v[148:151], v174
	ds_read_b128 v[224:227], v175
	ds_read_b128 v[228:231], v175 offset:2048
	ds_read_b128 v[232:235], v175 offset:4096
	ds_read_b128 v[236:239], v175 offset:6144
	s_waitcnt lgkmcnt(9)
	v_mfma_f32_16x16x32_bf16 v[90:93], v[152:155], v[208:211], v[90:93]
	v_mfma_f32_16x16x32_bf16 v[94:97], v[152:155], v[212:215], v[94:97]
	v_mfma_f32_16x16x32_bf16 v[74:77], v[152:155], v[216:219], v[74:77]
	v_mfma_f32_16x16x32_bf16 v[78:81], v[152:155], v[220:223], v[78:81]
	ds_read_b128 v[152:155], v174 offset:2048
	s_waitcnt lgkmcnt(9)
	v_mfma_f32_16x16x32_bf16 v[50:53], v[156:159], v[208:211], v[50:53]
	v_mfma_f32_16x16x32_bf16 v[54:57], v[156:159], v[212:215], v[54:57]
	v_mfma_f32_16x16x32_bf16 v[34:37], v[156:159], v[216:219], v[34:37]
	v_mfma_f32_16x16x32_bf16 v[38:41], v[156:159], v[220:223], v[38:41]
	ds_read_b128 v[156:159], v174 offset:4096
	s_waitcnt lgkmcnt(9)
	v_mfma_f32_16x16x32_bf16 v[58:61], v[160:163], v[208:211], v[58:61]
	v_mfma_f32_16x16x32_bf16 v[62:65], v[160:163], v[212:215], v[62:65]
	v_mfma_f32_16x16x32_bf16 v[42:45], v[160:163], v[216:219], v[42:45]
	v_mfma_f32_16x16x32_bf16 v[46:49], v[160:163], v[220:223], v[46:49]
	ds_read_b128 v[160:163], v174 offset:6144
	s_waitcnt lgkmcnt(9)
	v_mfma_f32_16x16x32_bf16 v[18:21], v[164:167], v[208:211], v[18:21]
	v_mfma_f32_16x16x32_bf16 v[22:25], v[164:167], v[212:215], v[22:25]
	v_mfma_f32_16x16x32_bf16 v[2:5], v[164:167], v[216:219], v[2:5]
	v_mfma_f32_16x16x32_bf16 v[6:9], v[164:167], v[220:223], v[6:9]
	ds_read_b128 v[164:167], v174 offset:8192
	s_waitcnt lgkmcnt(9)
	v_mfma_f32_16x16x32_bf16 v[26:29], v[168:171], v[208:211], v[26:29]
	v_mfma_f32_16x16x32_bf16 v[30:33], v[168:171], v[212:215], v[30:33]
	v_mfma_f32_16x16x32_bf16 v[10:13], v[168:171], v[216:219], v[10:13]
	v_mfma_f32_16x16x32_bf16 v[14:17], v[168:171], v[220:223], v[14:17]
	ds_read_b128 v[168:171], v174 offset:10240
	s_waitcnt lgkmcnt(5)
	v_mfma_f32_16x16x32_bf16 v[82:85], v[148:151], v[224:227], v[82:85]
	v_mfma_f32_16x16x32_bf16 v[86:89], v[148:151], v[228:231], v[86:89]
	v_mfma_f32_16x16x32_bf16 v[66:69], v[148:151], v[232:235], v[66:69]
	v_mfma_f32_16x16x32_bf16 v[70:73], v[148:151], v[236:239], v[70:73]
	s_waitcnt lgkmcnt(4)
	v_mfma_f32_16x16x32_bf16 v[90:93], v[152:155], v[224:227], v[90:93]
	v_mfma_f32_16x16x32_bf16 v[94:97], v[152:155], v[228:231], v[94:97]
	v_mfma_f32_16x16x32_bf16 v[74:77], v[152:155], v[232:235], v[74:77]
	v_mfma_f32_16x16x32_bf16 v[78:81], v[152:155], v[236:239], v[78:81]
	s_waitcnt lgkmcnt(3)
	v_mfma_f32_16x16x32_bf16 v[50:53], v[156:159], v[224:227], v[50:53]
	v_mfma_f32_16x16x32_bf16 v[54:57], v[156:159], v[228:231], v[54:57]
	v_mfma_f32_16x16x32_bf16 v[34:37], v[156:159], v[232:235], v[34:37]
	v_mfma_f32_16x16x32_bf16 v[38:41], v[156:159], v[236:239], v[38:41]
	s_waitcnt lgkmcnt(2)
	v_mfma_f32_16x16x32_bf16 v[58:61], v[160:163], v[224:227], v[58:61]
	v_mfma_f32_16x16x32_bf16 v[62:65], v[160:163], v[228:231], v[62:65]
	v_mfma_f32_16x16x32_bf16 v[42:45], v[160:163], v[232:235], v[42:45]
	v_mfma_f32_16x16x32_bf16 v[46:49], v[160:163], v[236:239], v[46:49]
	s_waitcnt lgkmcnt(1)
	v_mfma_f32_16x16x32_bf16 v[18:21], v[164:167], v[224:227], v[18:21]
	v_mfma_f32_16x16x32_bf16 v[22:25], v[164:167], v[228:231], v[22:25]
	v_mfma_f32_16x16x32_bf16 v[2:5], v[164:167], v[232:235], v[2:5]
	v_mfma_f32_16x16x32_bf16 v[6:9], v[164:167], v[236:239], v[6:9]
	s_waitcnt lgkmcnt(0)
	v_mfma_f32_16x16x32_bf16 v[26:29], v[168:171], v[224:227], v[26:29]
	v_mfma_f32_16x16x32_bf16 v[30:33], v[168:171], v[228:231], v[30:33]
	v_mfma_f32_16x16x32_bf16 v[10:13], v[168:171], v[232:235], v[10:13]
	v_mfma_f32_16x16x32_bf16 v[14:17], v[168:171], v[236:239], v[14:17]
	s_add_i32 s34, s34, 1
	s_add_u32 s2, s2, 0x80
	s_addc_u32 s3, s3, 0
	s_waitcnt vmcnt(0)
	s_barrier
	s_cmp_ge_u32 s34, s84
	s_cbranch_scc0 .Lgk_main
